# v18 + phase-1 norm loop software-pipelined across units: next unit's x rows prefetched into shadow registers after the unit's last vmcnt wait, counted wait at the loop top, gate bias loaded once, pos-
# baseline (speedup 1.0000x reference)
.LBB0_127:
	s_or_b64 exec, exec, s[4:5]
	s_waitcnt lgkmcnt(0)
	s_barrier
	s_load_dwordx2 s[16:17], s[0:1], 0x108
	v_mov_b32_e32 v0, v234
	s_cmpk_gt_i32 s2, 0x5ff
	s_cbranch_scc1 .LBB0_157
	s_load_dwordx4 s[8:11], s[0:1], 0x48
	v_ashrrev_i32_e32 v1, 2, v0
	s_mov_b32 s6, 0x9040
	v_lshlrev_b32_e32 v4, 4, v0
	v_and_b32_e32 v32, 48, v4
	s_waitcnt lgkmcnt(0)
	v_mov_b64_e32 v[30:31], s[10:11]
	v_mad_i64_i32 v[2:3], s[4:5], v1, s6, v[30:31]
	v_mov_b32_e32 v33, 0
	v_lshl_add_u64 v[2:3], v[2:3], 0, v[32:33]
	s_movk_i32 s7, 0x4000
	v_add_u32_e32 v1, 0x200, v0
	v_add_co_u32_e32 v10, vcc, s7, v2
	v_ashrrev_i32_e32 v2, 2, v1
	s_nop 0
	v_addc_co_u32_e32 v11, vcc, 0, v3, vcc
	v_mad_i64_i32 v[2:3], s[4:5], v2, s6, v[30:31]
	v_lshl_add_u64 v[2:3], v[2:3], 0, v[32:33]
	v_add_co_u32_e32 v12, vcc, s7, v2
	v_add_u32_e32 v38, 0x400, v0
	s_nop 0
	v_addc_co_u32_e32 v13, vcc, 0, v3, vcc
	global_load_dwordx4 v[2:5], v[10:11], off
	global_load_dwordx4 v[6:9], v[12:13], off
	v_ashrrev_i32_e32 v10, 2, v38
	v_mad_i64_i32 v[10:11], s[4:5], v10, s6, v[30:31]
	v_lshl_add_u64 v[10:11], v[10:11], 0, v[32:33]
	v_add_u32_e32 v39, 0x600, v0
	v_add_co_u32_e32 v18, vcc, s7, v10
	v_ashrrev_i32_e32 v10, 2, v39
	s_nop 0
	v_addc_co_u32_e32 v19, vcc, 0, v11, vcc
	v_mad_i64_i32 v[10:11], s[4:5], v10, s6, v[30:31]
	v_lshl_add_u64 v[10:11], v[10:11], 0, v[32:33]
	v_add_co_u32_e32 v20, vcc, s7, v10
	v_add_u32_e32 v40, 0x800, v0
	s_nop 0
	v_addc_co_u32_e32 v21, vcc, 0, v11, vcc
	global_load_dwordx4 v[10:13], v[18:19], off
	global_load_dwordx4 v[14:17], v[20:21], off
	v_ashrrev_i32_e32 v18, 2, v40
	v_mad_i64_i32 v[18:19], s[4:5], v18, s6, v[30:31]
	v_lshl_add_u64 v[18:19], v[18:19], 0, v[32:33]
	v_add_u32_e32 v41, 0xa00, v0
	v_add_co_u32_e32 v26, vcc, s7, v18
	v_ashrrev_i32_e32 v18, 2, v41
	s_nop 0
	v_addc_co_u32_e32 v27, vcc, 0, v19, vcc
	v_mad_i64_i32 v[18:19], s[4:5], v18, s6, v[30:31]
	v_lshl_add_u64 v[18:19], v[18:19], 0, v[32:33]
	v_add_co_u32_e32 v28, vcc, s7, v18
	v_add_u32_e32 v42, 0xc00, v0
	s_nop 0
	v_addc_co_u32_e32 v29, vcc, 0, v19, vcc
	global_load_dwordx4 v[18:21], v[26:27], off
	global_load_dwordx4 v[22:25], v[28:29], off
	v_ashrrev_i32_e32 v26, 2, v42
	v_mad_i64_i32 v[26:27], s[4:5], v26, s6, v[30:31]
	v_add_u32_e32 v43, 0xe00, v0
	v_lshl_add_u64 v[26:27], v[26:27], 0, v[32:33]
	v_ashrrev_i32_e32 v34, 2, v43
	v_add_co_u32_e32 v26, vcc, s7, v26
	v_mad_i64_i32 v[30:31], s[4:5], v34, s6, v[30:31]
	s_nop 0
	v_addc_co_u32_e32 v27, vcc, 0, v27, vcc
	v_lshl_add_u64 v[30:31], v[30:31], 0, v[32:33]
	global_load_dwordx4 v[26:29], v[26:27], off
	v_add_co_u32_e32 v30, vcc, s7, v30
	s_load_dwordx2 s[10:11], s[0:1], 0x58
	s_nop 0
	v_addc_co_u32_e32 v31, vcc, 0, v31, vcc
	global_load_dwordx4 v[34:37], v[30:31], off
	v_lshlrev_b32_e32 v30, 14, v0
	v_and_b32_e32 v30, 0xc000, v30
	v_add_u32_e32 v30, 0, v30
	v_and_b32_e32 v0, -4, v0
	v_add_u32_e32 v0, v30, v0
	s_add_u32 s18, s16, 0xe800000
	s_addc_u32 s19, s17, 0
	s_waitcnt vmcnt(7)
	ds_write2st64_b32 v0, v2, v3 offset1:16
	ds_write2st64_b32 v0, v4, v5 offset0:32 offset1:48
	v_and_b32_e32 v0, -4, v1
	v_add_u32_e32 v0, v30, v0
	s_waitcnt vmcnt(6)
	ds_write2st64_b32 v0, v6, v7 offset1:16
	ds_write2st64_b32 v0, v8, v9 offset0:32 offset1:48
	v_and_b32_e32 v0, -4, v38
	v_add_u32_e32 v0, v30, v0
	s_waitcnt vmcnt(5)
	ds_write2st64_b32 v0, v10, v11 offset1:16
	ds_write2st64_b32 v0, v12, v13 offset0:32 offset1:48
	v_and_b32_e32 v0, -4, v39
	v_add_u32_e32 v0, v30, v0
	s_waitcnt vmcnt(4)
	ds_write2st64_b32 v0, v14, v15 offset1:16
	ds_write2st64_b32 v0, v16, v17 offset0:32 offset1:48
	v_and_b32_e32 v0, -4, v40
	v_add_u32_e32 v0, v30, v0
	s_waitcnt vmcnt(3)
	ds_write2st64_b32 v0, v18, v19 offset1:16
	ds_write2st64_b32 v0, v20, v21 offset0:32 offset1:48
	v_and_b32_e32 v0, -4, v41
	v_add_u32_e32 v0, v30, v0
	s_waitcnt vmcnt(2)
	ds_write2st64_b32 v0, v22, v23 offset1:16
	ds_write2st64_b32 v0, v24, v25 offset0:32 offset1:48
	v_and_b32_e32 v0, -4, v42
	v_add_u32_e32 v0, v30, v0
	s_waitcnt vmcnt(1)
	ds_write2st64_b32 v0, v26, v27 offset1:16
	ds_write2st64_b32 v0, v28, v29 offset0:32 offset1:48
	v_and_b32_e32 v0, -4, v43
	v_add_u32_e32 v0, v30, v0
	s_add_u32 s20, s16, 0xe8ea000
	s_waitcnt vmcnt(0)
	ds_write2st64_b32 v0, v34, v35 offset1:16
	ds_write2st64_b32 v0, v36, v37 offset0:32 offset1:48
	s_waitcnt lgkmcnt(0)
	s_barrier
	s_addc_u32 s21, s17, 0
	s_load_dwordx4 s[12:15], s[0:1], 0x0
	s_add_u32 s22, s16, 0x2800000
	s_addc_u32 s23, s17, 0
	s_add_u32 s24, s16, 0xe91a000
	v_mbcnt_lo_u32_b32 v0, -1, 0
	s_addc_u32 s25, s17, 0
	s_lshl_b32 s30, s2, 4
	s_lshl_b32 s31, s56, 4
	s_movk_i32 s33, 0x1fff
	s_movk_i32 s34, 0x2000
	v_mov_b32_e32 v50, 0x358637bd
	s_mov_b32 s35, 0x800000
	s_movk_i32 s36, 0x1800
	s_mov_b64 s[26:27], 0x1000
	v_mbcnt_hi_u32_b32 v51, -1, v0
	s_mov_b32 s37, s2
	v_lshrrev_b32_e32 v252, 6, v234
	v_and_b32_e32 v253, 63, v234
	v_lshlrev_b32_e32 v252, 13, v252
	v_lshl_or_b32 v252, v253, 4, v252
	v_add_u32_e32 v253, 0x1000, v252
	s_waitcnt lgkmcnt(0)
	v_and_b32_e32 v250, 15, v234
	v_lshlrev_b32_e32 v250, 2, v250
	v_add_u32_e32 v250, 0x4000, v250
	s_cmpk_lt_i32 s37, 0x200
	s_cselect_b32 s40, s12, s14
	s_cselect_b32 s41, s13, s15
	s_cselect_b32 s42, 0, 0x2000
	s_sub_i32 s39, s30, s42
	s_lshl_b32 s39, s39, 12
	s_add_u32 s40, s40, s39
	s_addc_u32 s41, s41, 0
	global_load_dwordx4 v[188:191], v252, s[40:41]
	global_load_dwordx4 v[192:195], v252, s[40:41] offset:1024
	global_load_dwordx4 v[196:199], v252, s[40:41] offset:2048
	global_load_dwordx4 v[200:203], v252, s[40:41] offset:3072
	global_load_dwordx4 v[204:207], v253, s[40:41]
	global_load_dwordx4 v[208:211], v253, s[40:41] offset:1024
	global_load_dwordx4 v[212:215], v253, s[40:41] offset:2048
	global_load_dwordx4 v[216:219], v253, s[40:41] offset:3072
	global_load_dword v251, v250, s[10:11]
	s_branch .LBB0_130

.LBB0_130:
	v_mov_b32_e32 v37, v234
	s_nop 0
	v_ashrrev_i32_e32 v0, 5, v37
	v_and_b32_e32 v0, -2, v0
	v_add_u32_e32 v34, s30, v0
	v_cmp_lt_i32_e64 s[4:5], s33, v34
	v_cmp_gt_i32_e64 s[6:7], s34, v34
	v_ashrrev_i32_e32 v35, 31, v34
	s_sub_i32 s46, s37, s56
	s_cmpk_lt_i32 s46, 0x200
	s_cselect_b64 s[44:45], s[4:5], 0
	s_cmpk_eq_i32 s56, 0x100
	s_cselect_b64 s[44:45], s[44:45], s[4:5]
	s_and_saveexec_b64 s[28:29], s[6:7]
	s_xor_b64 s[28:29], exec, s[28:29]
	s_cbranch_execz .LBB0_132
	v_lshlrev_b64 v[0:1], 12, v[34:35]
	s_waitcnt lgkmcnt(0)
	v_lshl_add_u64 v[0:1], s[12:13], 0, v[0:1]

.LBB0_134:
	s_or_b64 exec, exec, s[28:29]
	v_lshlrev_b32_e32 v2, 5, v4
	v_and_b32_e32 v52, 63, v37
	v_and_b32_e32 v32, 0xf800, v2
	v_lshl_add_u64 v[2:3], s[20:21], 0, v[32:33]
	v_lshlrev_b32_e32 v32, 4, v52
	v_lshl_add_u64 v[0:1], v[0:1], 0, v[32:33]
	v_lshlrev_b32_e32 v36, 2, v52
	v_lshlrev_b32_e32 v32, 2, v36
	s_and_saveexec_b64 s[28:29], s[44:45]
	s_cbranch_execz .LBB0_136
	v_lshl_add_u64 v[6:7], v[2:3], 0, v[32:33]
	global_load_dwordx4 v[132:135], v[6:7], off
.LBB0_136:
	s_or_b64 exec, exec, s[28:29]
	s_and_saveexec_b64 s[28:29], s[44:45]
	s_cbranch_execz .LBB0_138
	v_lshl_add_u64 v[2:3], v[2:3], 0, v[32:33]
	global_load_dwordx4 v[136:139], v[2:3], off offset:1024
.LBB0_138:
	s_or_b64 exec, exec, s[28:29]
	v_lshlrev_b32_e32 v2, 11, v4
	v_and_b32_e32 v2, 0x1f000, v2
	v_mov_b32_e32 v3, v33
	v_lshl_add_u64 v[4:5], s[16:17], 0, v[2:3]
	s_and_saveexec_b64 s[28:29], s[44:45]
	s_cbranch_execz .LBB0_140
	v_lshl_add_u64 v[2:3], v[4:5], 0, v[32:33]
	v_add_co_u32_e32 v2, vcc, 0xe8fa000, v2
	s_nop 1
	v_addc_co_u32_e32 v3, vcc, 0, v3, vcc
	global_load_dwordx4 v[140:143], v[2:3], off
.LBB0_140:
	s_or_b64 exec, exec, s[28:29]
	s_and_saveexec_b64 s[28:29], s[44:45]
	s_cbranch_execz .LBB0_142
	v_lshl_add_u64 v[4:5], v[4:5], 0, v[32:33]
	v_add_co_u32_e32 v4, vcc, 0xe8fa000, v4
	s_nop 1
	v_addc_co_u32_e32 v5, vcc, 0, v5, vcc
	global_load_dwordx4 v[144:147], v[4:5], off offset:1024

.LBB0_146:
	s_or_b64 exec, exec, s[6:7]
	v_lshl_add_u64 v[4:5], v[4:5], 0, v[32:33]
	v_lshlrev_b32_e32 v6, 5, v39
	v_and_b32_e32 v6, 0xf800, v6
	v_mov_b32_e32 v7, v33
	v_lshl_add_u64 v[6:7], s[20:21], 0, v[6:7]
	s_and_saveexec_b64 s[6:7], s[44:45]
	s_cbranch_execz .LBB0_148
	v_lshl_add_u64 v[12:13], v[6:7], 0, v[32:33]
	global_load_dwordx4 v[148:151], v[12:13], off
.LBB0_148:
	s_or_b64 exec, exec, s[6:7]
	s_and_saveexec_b64 s[6:7], s[44:45]
	s_cbranch_execz .LBB0_150
	v_lshl_add_u64 v[6:7], v[6:7], 0, v[32:33]
	global_load_dwordx4 v[152:155], v[6:7], off offset:1024
.LBB0_150:
	s_or_b64 exec, exec, s[6:7]
	v_lshlrev_b32_e32 v6, 11, v39
	v_and_b32_e32 v6, 0x1f800, v6
	v_mov_b32_e32 v7, v33
	v_lshl_add_u64 v[40:41], s[16:17], 0, v[6:7]
	s_and_saveexec_b64 s[6:7], s[44:45]
	s_cbranch_execz .LBB0_152
	v_lshl_add_u64 v[6:7], v[40:41], 0, v[32:33]
	v_add_co_u32_e32 v6, vcc, 0xe8fa000, v6
	s_nop 1
	v_addc_co_u32_e32 v7, vcc, 0, v7, vcc
	global_load_dwordx4 v[156:159], v[6:7], off
.LBB0_152:
	s_or_b64 exec, exec, s[6:7]
	s_and_saveexec_b64 s[6:7], s[44:45]
	s_cbranch_execz .LBB0_154
	v_lshl_add_u64 v[40:41], v[40:41], 0, v[32:33]
	v_add_co_u32_e32 v40, vcc, 0xe8fa000, v40
	s_nop 1
	v_addc_co_u32_e32 v41, vcc, 0, v41, vcc
	global_load_dwordx4 v[168:171], v[40:41], off offset:1024
.LBB0_154:
	s_or_b64 exec, exec, s[6:7]
	s_cmp_lg_u64 s[44:45], 0
	s_cbranch_scc1 .Lp1_w0
	s_waitcnt vmcnt(1)
	s_branch .Lp1_wd

.Lp1_wd:
	v_mov_b64_e32 v[24:25], v[188:189]
	v_mov_b64_e32 v[26:27], v[190:191]
	v_mov_b64_e32 v[16:17], v[192:193]
	v_mov_b64_e32 v[18:19], v[194:195]
	v_mov_b64_e32 v[8:9], v[196:197]
	v_mov_b64_e32 v[10:11], v[198:199]
	v_mov_b64_e32 v[0:1], v[200:201]
	v_mov_b64_e32 v[2:3], v[202:203]
	v_mov_b64_e32 v[28:29], v[204:205]
	v_mov_b64_e32 v[30:31], v[206:207]
	v_mov_b64_e32 v[20:21], v[208:209]
	v_mov_b64_e32 v[22:23], v[210:211]
	v_mov_b64_e32 v[12:13], v[212:213]
	v_mov_b64_e32 v[14:15], v[214:215]
	v_mov_b64_e32 v[4:5], v[216:217]
	v_mov_b64_e32 v[6:7], v[218:219]
	s_and_saveexec_b64 s[28:29], s[4:5]
	s_cbranch_execz .Lp1_r0_ctx
	s_waitcnt vmcnt(8)
	v_pk_add_f32 v[26:27], v[26:27], v[134:135]
	v_pk_add_f32 v[24:25], v[24:25], v[132:133]
	v_pk_add_f32 v[18:19], v[18:19], v[138:139]
	v_pk_add_f32 v[16:17], v[16:17], v[136:137]
	v_pk_add_f32 v[10:11], v[10:11], v[142:143]
	v_pk_add_f32 v[8:9], v[8:9], v[140:141]
	v_pk_add_f32 v[2:3], v[2:3], v[146:147]
	v_pk_add_f32 v[0:1], v[0:1], v[144:145]
	s_or_b64 exec, exec, s[28:29]
	s_branch .Lp1_r0_join

.Lp1_r0_join:
	v_mul_f32_e32 v166, v25, v25
	v_mul_f32_e32 v167, v17, v17
	v_fmac_f32_e32 v166, v24, v24
	v_fmac_f32_e32 v167, v16, v16
	v_fmac_f32_e32 v166, v26, v26
	v_fmac_f32_e32 v167, v18, v18
	v_fmac_f32_e32 v166, v27, v27
	v_fmac_f32_e32 v167, v19, v19
	v_add_f32_e32 v166, v166, v167
	v_mul_f32_e32 v167, v9, v9
	v_fmac_f32_e32 v167, v8, v8
	v_fmac_f32_e32 v167, v10, v10
	v_fmac_f32_e32 v167, v11, v11
	v_add_f32_e32 v166, v166, v167
	v_mul_f32_e32 v167, v1, v1
	v_fmac_f32_e32 v167, v0, v0
	v_fmac_f32_e32 v167, v2, v2
	v_fmac_f32_e32 v167, v3, v3
	v_add_f32_e32 v166, v166, v167
	s_nop 1
	v_add_f32_dpp v166, v166, v166 quad_perm:[1,0,3,2] row_mask:0xf bank_mask:0xf bound_ctrl:1
	s_nop 1
	v_add_f32_dpp v166, v166, v166 quad_perm:[2,3,0,1] row_mask:0xf bank_mask:0xf bound_ctrl:1
	s_nop 1
	v_add_f32_dpp v166, v166, v166 row_half_mirror row_mask:0xf bank_mask:0xf bound_ctrl:1
	s_nop 1
	v_add_f32_dpp v166, v166, v166 row_ror:8 row_mask:0xf bank_mask:0xf bound_ctrl:1
	v_mov_b32_e32 v167, v166
	s_nop 1
	v_permlane16_swap_b32_e32 v166, v167
	v_add_f32_e32 v44, v166, v167
	v_mov_b32_e32 v45, v44
	s_nop 1
	v_permlane32_swap_b32_e32 v44, v45
	s_and_saveexec_b64 s[6:7], s[4:5]
	s_cbranch_execz .Lp1_r1_ctx
	v_pk_add_f32 v[30:31], v[30:31], v[150:151]
	v_pk_add_f32 v[28:29], v[28:29], v[148:149]
	v_pk_add_f32 v[22:23], v[22:23], v[154:155]
	v_pk_add_f32 v[20:21], v[20:21], v[152:153]
	v_pk_add_f32 v[14:15], v[14:15], v[158:159]
	v_pk_add_f32 v[12:13], v[12:13], v[156:157]
	v_pk_add_f32 v[6:7], v[6:7], v[170:171]
	v_pk_add_f32 v[4:5], v[4:5], v[168:169]
.Lp1_r1_ctx:
	s_or_b64 exec, exec, s[6:7]
	v_lshrrev_b32_e32 v38, 11, v38
	v_mad_u32_u24 v38, v38, s36, s36
	v_cmp_lt_i32_e32 vcc, s33, v34
	v_mov_b32_e32 v39, v33
	s_waitcnt vmcnt(3)
	v_mul_f32_e32 v80, v29, v29
	v_cndmask_b32_e32 v38, 0, v38, vcc
	v_lshl_add_u64 v[40:41], v[38:39], 2, s[18:19]
	v_lshl_add_u64 v[38:39], v[40:41], 0, s[26:27]
	v_lshl_add_u64 v[46:47], v[38:39], 0, v[32:33]
	global_load_dwordx4 v[56:59], v[46:47], off
	global_load_dwordx4 v[60:63], v32, s[8:9]
	v_lshl_add_u64 v[40:41], v[40:41], 0, v[32:33]
	global_load_dwordx4 v[64:67], v[40:41], off
	s_waitcnt vmcnt(5)
	v_mul_f32_e32 v81, v21, v21
	s_waitcnt vmcnt(4)
	v_mul_f32_e32 v82, v13, v13
	v_fmac_f32_e32 v80, v28, v28
	v_fmac_f32_e32 v81, v20, v20
	s_waitcnt vmcnt(3)
	v_mul_f32_e32 v83, v5, v5
	v_lshlrev_b32_e32 v48, 1, v36
	v_mov_b32_e32 v49, v33
	v_fmac_f32_e32 v82, v12, v12
	v_fmac_f32_e32 v80, v30, v30
	v_fmac_f32_e32 v81, v22, v22
	v_add_f32_e32 v68, v44, v45
	v_lshlrev_b64 v[46:47], 11, v[34:35]
	v_lshlrev_b64 v[44:45], 11, v[42:43]
	v_fmac_f32_e32 v83, v4, v4
	v_lshl_add_u64 v[48:49], s[22:23], 0, v[48:49]
	v_fmac_f32_e32 v82, v14, v14
	v_fmac_f32_e32 v80, v31, v31
	v_fmac_f32_e32 v81, v23, v23
	v_fmac_f32_e32 v83, v6, v6
	v_lshl_add_u64 v[76:77], v[48:49], 0, v[46:47]
	v_lshl_add_u64 v[78:79], v[48:49], 0, v[44:45]
	v_fmac_f32_e32 v82, v15, v15
	v_add_f32_e32 v48, v80, v81
	v_fmac_f32_e32 v83, v7, v7
	v_add_f32_e32 v48, v48, v82
	v_add_f32_e32 v48, v48, v83
	v_fmamk_f32 v42, v68, 0x3a800000, v50
	v_mul_f32_e32 v84, 0x4b800000, v42
	v_add_f32_dpp v48, v48, v48 quad_perm:[1,0,3,2] row_mask:0xf bank_mask:0xf bound_ctrl:1
	v_cmp_gt_f32_e32 vcc, s35, v42
	v_lshl_add_u32 v43, v36, 2, 0
	v_add_f32_dpp v48, v48, v48 quad_perm:[2,3,0,1] row_mask:0xf bank_mask:0xf bound_ctrl:1
	v_cndmask_b32_e32 v42, v42, v84, vcc
	v_rsq_f32_e32 v42, v42
	v_add_f32_dpp v48, v48, v48 row_half_mirror row_mask:0xf bank_mask:0xf bound_ctrl:1
	ds_read_b128 v[68:71], v43
	ds_read_b128 v[72:75], v43 offset:4096
	v_add_f32_dpp v48, v48, v48 row_ror:8 row_mask:0xf bank_mask:0xf bound_ctrl:1
	v_mov_b32_e32 v80, v48
	s_nop 1
	v_permlane16_swap_b32_e32 v48, v80
	v_add_f32_e32 v48, v48, v80
	v_mov_b32_e32 v80, v48
	s_nop 1
	v_permlane32_swap_b32_e32 v48, v80
	v_add_f32_e32 v48, v48, v80
	v_fmamk_f32 v48, v48, 0x3a800000, v50
	v_mul_f32_e32 v80, 0x4b800000, v48
	v_cmp_gt_f32_e64 s[4:5], s35, v48
	v_mul_f32_e32 v49, 0x45800000, v42
	v_cndmask_b32_e32 v42, v42, v49, vcc
	v_cndmask_b32_e64 v48, v48, v80, s[4:5]
	v_rsq_f32_e32 v80, v48
	v_pk_mul_f32 v[48:49], v[24:25], v[42:43] op_sel_hi:[1,0]
	v_pk_mul_f32 v[26:27], v[26:27], v[42:43] op_sel_hi:[1,0]
	v_or_b32_e32 v55, 0x100, v36
	v_mul_f32_e32 v24, 0x45800000, v80
	v_cndmask_b32_e64 v24, v80, v24, s[4:5]
	v_pk_mul_f32 v[80:81], v[28:29], v[24:25] op_sel_hi:[1,0]
	v_pk_mul_f32 v[30:31], v[30:31], v[24:25] op_sel_hi:[1,0]
	v_lshlrev_b32_e32 v88, 2, v55
	v_mov_b32_e32 v89, v33
	v_lshl_add_u64 v[88:89], v[38:39], 0, v[88:89]
	v_pk_mul_f32 v[16:17], v[16:17], v[42:43] op_sel_hi:[1,0]
	v_pk_mul_f32 v[18:19], v[18:19], v[42:43] op_sel_hi:[1,0]
	v_or_b32_e32 v54, 0x200, v36
	v_or_b32_e32 v53, 0x300, v36
	s_waitcnt vmcnt(2)
	v_pk_add_f32 v[28:29], v[58:59], 1.0 op_sel_hi:[1,0]
	v_pk_add_f32 v[56:57], v[56:57], 1.0 op_sel_hi:[1,0]
	s_waitcnt vmcnt(1)
	v_pk_mul_f32 v[58:59], v[62:63], v[28:29]
	v_pk_mul_f32 v[56:57], v[60:61], v[56:57]
	s_waitcnt vmcnt(0)
	v_pk_fma_f32 v[28:29], v[26:27], v[58:59], v[66:67]
	v_pk_fma_f32 v[48:49], v[48:49], v[56:57], v[64:65]
	v_pk_fma_f32 v[26:27], v[58:59], v[30:31], v[66:67]
	v_pk_fma_f32 v[30:31], v[56:57], v[80:81], v[64:65]
	v_cvt_pk_bf16_f32 v56, v48, v49
	v_cvt_pk_bf16_f32 v57, v28, v29
	v_cvt_pk_bf16_f32 v58, v30, v31
	v_cvt_pk_bf16_f32 v59, v26, v27
	global_store_dwordx2 v[76:77], v[56:57], off
	global_store_dwordx2 v[78:79], v[58:59], off
	s_waitcnt lgkmcnt(0)
	v_mul_f32_e32 v56, v69, v31
	v_fmac_f32_e32 v56, v68, v30
	v_fmac_f32_e32 v56, v70, v26
	v_fmac_f32_e32 v56, v71, v27
	v_add_f32_e32 v100, 0, v56
	v_mul_f32_e32 v56, v49, v73
	v_fmac_f32_e32 v56, v48, v72
	v_mul_f32_e32 v60, v73, v31
	v_fmac_f32_e32 v56, v28, v74
	v_fmac_f32_e32 v60, v72, v30
	v_fmac_f32_e32 v56, v29, v75
	v_fmac_f32_e32 v60, v74, v26
	v_add_f32_e32 v101, 0, v56
	ds_read_b128 v[56:59], v43 offset:8192
	v_fmac_f32_e32 v60, v75, v27
	v_add_f32_e32 v102, 0, v60
	ds_read_b128 v[60:63], v43 offset:12288
	v_mul_f32_e32 v25, v69, v49
	s_waitcnt lgkmcnt(1)
	v_mul_f32_e32 v64, v49, v57
	v_mul_f32_e32 v57, v57, v31
	v_fmac_f32_e32 v64, v48, v56
	v_fmac_f32_e32 v57, v56, v30
	s_waitcnt lgkmcnt(0)
	v_mul_f32_e32 v56, v49, v61
	v_fmac_f32_e32 v56, v48, v60
	v_mul_f32_e32 v61, v61, v31
	v_fmac_f32_e32 v57, v58, v26
	v_fmac_f32_e32 v56, v28, v62
	v_fmac_f32_e32 v61, v60, v30
	v_fmac_f32_e32 v64, v28, v58
	v_fmac_f32_e32 v57, v59, v27
	v_fmac_f32_e32 v56, v29, v63
	v_fmac_f32_e32 v61, v62, v26
	v_fmac_f32_e32 v64, v29, v59
	v_add_f32_e32 v104, 0, v57
	v_add_f32_e32 v105, 0, v56
	ds_read_b128 v[56:59], v43 offset:16384
	v_fmac_f32_e32 v61, v63, v27
	v_add_f32_e32 v106, 0, v61
	ds_read_b128 v[60:63], v43 offset:20480
	v_add_f32_e32 v103, 0, v64
	s_waitcnt lgkmcnt(1)
	v_mul_f32_e32 v64, v49, v57
	v_mul_f32_e32 v57, v57, v31
	v_fmac_f32_e32 v64, v48, v56
	v_fmac_f32_e32 v57, v56, v30
	s_waitcnt lgkmcnt(0)
	v_mul_f32_e32 v56, v49, v61
	v_fmac_f32_e32 v56, v48, v60
	v_mul_f32_e32 v61, v61, v31
	v_fmac_f32_e32 v57, v58, v26
	v_fmac_f32_e32 v56, v28, v62
	v_fmac_f32_e32 v61, v60, v30
	v_fmac_f32_e32 v64, v28, v58
	v_fmac_f32_e32 v57, v59, v27
	v_fmac_f32_e32 v56, v29, v63
	v_fmac_f32_e32 v61, v62, v26
	v_fmac_f32_e32 v64, v29, v59
	v_add_f32_e32 v108, 0, v57
	v_add_f32_e32 v109, 0, v56
	ds_read_b128 v[56:59], v43 offset:24576
	v_fmac_f32_e32 v61, v63, v27
	v_add_f32_e32 v110, 0, v61
	ds_read_b128 v[60:63], v43 offset:28672
	v_add_f32_e32 v107, 0, v64
	s_waitcnt lgkmcnt(1)
	v_mul_f32_e32 v64, v49, v57
	v_mul_f32_e32 v57, v57, v31
	v_fmac_f32_e32 v64, v48, v56
	v_fmac_f32_e32 v57, v56, v30
	s_waitcnt lgkmcnt(0)
	v_mul_f32_e32 v56, v49, v61
	v_fmac_f32_e32 v56, v48, v60
	v_fmac_f32_e32 v57, v58, v26
	v_fmac_f32_e32 v56, v28, v62
	v_fmac_f32_e32 v64, v28, v58
	v_fmac_f32_e32 v57, v59, v27
	v_fmac_f32_e32 v56, v29, v63
	v_fmac_f32_e32 v64, v29, v59
	v_add_f32_e32 v112, 0, v57
	v_add_f32_e32 v113, 0, v56
	ds_read_b128 v[56:59], v43 offset:32768
	v_mul_f32_e32 v61, v61, v31
	v_fmac_f32_e32 v61, v60, v30
	v_fmac_f32_e32 v61, v62, v26
	v_fmac_f32_e32 v25, v68, v48
	v_fmac_f32_e32 v61, v63, v27
	v_fmac_f32_e32 v25, v70, v28
	v_add_f32_e32 v114, 0, v61
	ds_read_b128 v[60:63], v43 offset:36864
	s_waitcnt lgkmcnt(1)
	v_mul_f32_e32 v96, v49, v57
	v_fmac_f32_e32 v25, v71, v29
	v_add_f32_e32 v111, 0, v64
	v_fmac_f32_e32 v96, v48, v56
	ds_read_b128 v[64:67], v43 offset:40960
	ds_read_b128 v[68:71], v43 offset:45056
	ds_read_b128 v[72:75], v43 offset:49152
	ds_read_b128 v[76:79], v43 offset:53248
	ds_read_b128 v[80:83], v43 offset:57344
	ds_read_b128 v[84:87], v43 offset:61440
	v_fmac_f32_e32 v96, v28, v58
	global_load_dwordx4 v[88:91], v[88:89], off
	v_fmac_f32_e32 v96, v29, v59
	global_load_dwordx4 v[92:95], v32, s[8:9] offset:1024
	v_add_f32_e32 v115, 0, v96
	global_load_dwordx4 v[96:99], v[40:41], off offset:1024
	v_mul_f32_e32 v57, v57, v31
	v_fmac_f32_e32 v57, v56, v30
	s_waitcnt lgkmcnt(6)
	v_mul_f32_e32 v56, v49, v61
	v_fmac_f32_e32 v56, v48, v60
	v_fmac_f32_e32 v56, v28, v62
	v_fmac_f32_e32 v56, v29, v63
	v_add_f32_e32 v117, 0, v56
	v_mul_f32_e32 v56, v31, v61
	v_fmac_f32_e32 v56, v30, v60
	v_fmac_f32_e32 v56, v26, v62
	v_fmac_f32_e32 v56, v27, v63
	v_add_f32_e32 v118, 0, v56
	s_waitcnt lgkmcnt(5)
	v_mul_f32_e32 v56, v49, v65
	v_fmac_f32_e32 v56, v48, v64
	v_fmac_f32_e32 v56, v28, v66
	v_fmac_f32_e32 v56, v29, v67
	v_add_f32_e32 v119, 0, v56
	v_mul_f32_e32 v56, v31, v65
	v_fmac_f32_e32 v56, v30, v64
	v_fmac_f32_e32 v56, v26, v66
	v_fmac_f32_e32 v56, v27, v67
	v_add_f32_e32 v120, 0, v56
	s_waitcnt lgkmcnt(4)
	v_mul_f32_e32 v56, v49, v69
	v_fmac_f32_e32 v56, v48, v68
	v_fmac_f32_e32 v56, v28, v70
	v_fmac_f32_e32 v56, v29, v71
	v_add_f32_e32 v121, 0, v56
	v_mul_f32_e32 v56, v31, v69
	v_fmac_f32_e32 v56, v30, v68
	v_fmac_f32_e32 v56, v26, v70
	v_fmac_f32_e32 v56, v27, v71
	v_add_f32_e32 v122, 0, v56
	s_waitcnt lgkmcnt(3)
	v_mul_f32_e32 v56, v49, v73
	v_fmac_f32_e32 v56, v48, v72
	v_fmac_f32_e32 v56, v28, v74
	v_fmac_f32_e32 v56, v29, v75
	v_add_f32_e32 v123, 0, v56
	v_mul_f32_e32 v56, v31, v73
	v_fmac_f32_e32 v56, v30, v72
	v_fmac_f32_e32 v56, v26, v74
	v_fmac_f32_e32 v56, v27, v75
	v_add_f32_e32 v124, 0, v56
	s_waitcnt lgkmcnt(2)
	v_mul_f32_e32 v56, v49, v77
	v_fmac_f32_e32 v56, v48, v76
	v_fmac_f32_e32 v56, v28, v78
	v_fmac_f32_e32 v56, v29, v79
	v_add_f32_e32 v125, 0, v56
	v_mul_f32_e32 v56, v31, v77
	v_fmac_f32_e32 v56, v30, v76
	v_fmac_f32_e32 v56, v26, v78
	v_fmac_f32_e32 v56, v27, v79
	v_add_f32_e32 v126, 0, v56
	s_waitcnt lgkmcnt(1)
	v_mul_f32_e32 v56, v49, v81
	v_fmac_f32_e32 v56, v48, v80
	s_waitcnt lgkmcnt(0)
	v_mul_f32_e32 v49, v49, v85
	v_fmac_f32_e32 v56, v28, v82
	v_fmac_f32_e32 v49, v48, v84
	v_fmac_f32_e32 v56, v29, v83
	v_fmac_f32_e32 v49, v28, v86
	v_mul_f32_e32 v28, v31, v85
	v_add_f32_e32 v127, 0, v56
	v_mul_f32_e32 v56, v31, v81
	v_fmac_f32_e32 v28, v30, v84
	v_fmac_f32_e32 v56, v30, v80
	v_fmac_f32_e32 v28, v26, v86
	v_fmac_f32_e32 v57, v58, v26
	v_fmac_f32_e32 v56, v26, v82
	v_fmac_f32_e32 v28, v27, v87
	v_fmac_f32_e32 v57, v59, v27
	v_fmac_f32_e32 v56, v27, v83
	v_fmac_f32_e32 v49, v29, v87
	v_add_f32_e32 v130, 0, v28
	v_add_f32_e32 v129, 0, v49
	v_add_f32_e32 v116, 0, v57
	v_add_f32_e32 v128, 0, v56
	s_waitcnt vmcnt(2)
	v_pk_add_f32 v[26:27], v[90:91], 1.0 op_sel_hi:[1,0]
	v_pk_add_f32 v[28:29], v[88:89], 1.0 op_sel_hi:[1,0]
	s_waitcnt vmcnt(1)
	v_pk_mul_f32 v[30:31], v[94:95], v[26:27]
	v_pk_mul_f32 v[48:49], v[92:93], v[28:29]
	s_waitcnt vmcnt(0)
	v_pk_fma_f32 v[26:27], v[18:19], v[30:31], v[98:99]
	v_pk_fma_f32 v[28:29], v[16:17], v[48:49], v[96:97]
	v_lshl_add_u64 v[16:17], s[22:23], 0, v[46:47]
	v_lshlrev_b32_e32 v56, 1, v55
	v_mov_b32_e32 v57, v33
	v_add_f32_e32 v25, 0, v25
	v_cvt_pk_bf16_f32 v18, v28, v29
	v_cvt_pk_bf16_f32 v19, v26, v27
	v_lshl_add_u64 v[46:47], v[16:17], 0, v[56:57]
	global_store_dwordx2 v[46:47], v[18:19], off
	v_pk_mul_f32 v[18:19], v[20:21], v[24:25] op_sel_hi:[1,0]
	v_pk_mul_f32 v[20:21], v[22:23], v[24:25] op_sel_hi:[1,0]
	v_pk_fma_f32 v[22:23], v[18:19], v[48:49], v[96:97]
	ds_read_b128 v[46:49], v43 offset:1024
	v_pk_fma_f32 v[20:21], v[20:21], v[30:31], v[98:99]
	v_lshl_add_u64 v[18:19], s[22:23], 0, v[44:45]
	v_cvt_pk_bf16_f32 v30, v22, v23
	v_cvt_pk_bf16_f32 v31, v20, v21
	v_lshl_add_u64 v[44:45], v[18:19], 0, v[56:57]
	global_store_dwordx2 v[44:45], v[30:31], off
	ds_read_b128 v[56:59], v43 offset:5120
	s_waitcnt lgkmcnt(1)
	v_mul_f32_e32 v30, v47, v29
	v_fmac_f32_e32 v30, v46, v28
	v_fmac_f32_e32 v30, v48, v26
	v_fmac_f32_e32 v30, v49, v27
	v_add_f32_e32 v25, v25, v30
	v_mul_f32_e32 v30, v47, v23
	v_fmac_f32_e32 v30, v46, v22
	v_fmac_f32_e32 v30, v48, v20
	v_fmac_f32_e32 v30, v49, v21
	v_add_f32_e32 v48, v100, v30
	s_waitcnt lgkmcnt(0)
	v_mul_f32_e32 v30, v29, v57
	v_fmac_f32_e32 v30, v28, v56
	v_fmac_f32_e32 v30, v26, v58
	v_fmac_f32_e32 v30, v27, v59
	ds_read_b128 v[44:47], v43 offset:9216
	v_add_f32_e32 v49, v101, v30
	v_mul_f32_e32 v30, v23, v57
	v_fmac_f32_e32 v30, v22, v56
	v_fmac_f32_e32 v30, v20, v58
	v_fmac_f32_e32 v30, v21, v59
	v_add_f32_e32 v55, v102, v30
	ds_read_b128 v[56:59], v43 offset:13312
	s_waitcnt lgkmcnt(1)
	v_mul_f32_e32 v30, v29, v45
	v_fmac_f32_e32 v30, v28, v44
	v_fmac_f32_e32 v30, v26, v46
	v_fmac_f32_e32 v30, v27, v47
	v_add_f32_e32 v96, v103, v30
	v_mul_f32_e32 v30, v23, v45
	v_fmac_f32_e32 v30, v22, v44
	v_fmac_f32_e32 v30, v20, v46
	v_fmac_f32_e32 v30, v21, v47
	v_add_f32_e32 v97, v104, v30
	s_waitcnt lgkmcnt(0)
	v_mul_f32_e32 v30, v29, v57
	v_fmac_f32_e32 v30, v28, v56
	v_fmac_f32_e32 v30, v26, v58
	v_fmac_f32_e32 v30, v27, v59
	ds_read_b128 v[44:47], v43 offset:17408
	v_add_f32_e32 v98, v105, v30
	v_mul_f32_e32 v30, v23, v57
	v_fmac_f32_e32 v30, v22, v56
	v_fmac_f32_e32 v30, v20, v58
	v_fmac_f32_e32 v30, v21, v59
	v_add_f32_e32 v99, v106, v30
	ds_read_b128 v[56:59], v43 offset:21504
	s_waitcnt lgkmcnt(1)
	v_mul_f32_e32 v30, v29, v45
	v_fmac_f32_e32 v30, v28, v44
	v_fmac_f32_e32 v30, v26, v46
	v_fmac_f32_e32 v30, v27, v47
	v_add_f32_e32 v100, v107, v30
	v_mul_f32_e32 v30, v23, v45
	v_fmac_f32_e32 v30, v22, v44
	v_fmac_f32_e32 v30, v20, v46
	v_fmac_f32_e32 v30, v21, v47
	v_add_f32_e32 v101, v108, v30
	s_waitcnt lgkmcnt(0)
	v_mul_f32_e32 v30, v29, v57
	v_fmac_f32_e32 v30, v28, v56
	v_fmac_f32_e32 v30, v26, v58
	v_fmac_f32_e32 v30, v27, v59
	ds_read_b128 v[44:47], v43 offset:25600
	v_add_f32_e32 v102, v109, v30
	v_mul_f32_e32 v30, v23, v57
	v_fmac_f32_e32 v30, v22, v56
	v_fmac_f32_e32 v30, v20, v58
	v_fmac_f32_e32 v30, v21, v59
	v_add_f32_e32 v103, v110, v30
	ds_read_b128 v[56:59], v43 offset:29696
	s_waitcnt lgkmcnt(1)
	v_mul_f32_e32 v30, v29, v45
	v_fmac_f32_e32 v30, v28, v44
	v_fmac_f32_e32 v30, v26, v46
	v_fmac_f32_e32 v30, v27, v47
	v_add_f32_e32 v104, v111, v30
	v_mul_f32_e32 v30, v23, v45
	v_fmac_f32_e32 v30, v22, v44
	v_fmac_f32_e32 v30, v20, v46
	v_fmac_f32_e32 v30, v21, v47
	v_add_f32_e32 v105, v112, v30
	s_waitcnt lgkmcnt(0)
	v_mul_f32_e32 v30, v29, v57
	v_fmac_f32_e32 v30, v28, v56
	v_fmac_f32_e32 v30, v26, v58
	v_fmac_f32_e32 v30, v27, v59
	ds_read_b128 v[44:47], v43 offset:33792
	v_add_f32_e32 v106, v113, v30
	v_mul_f32_e32 v30, v23, v57
	v_fmac_f32_e32 v30, v22, v56
	v_fmac_f32_e32 v30, v20, v58
	v_fmac_f32_e32 v30, v21, v59
	v_add_f32_e32 v107, v114, v30
	ds_read_b128 v[56:59], v43 offset:37888
	s_waitcnt lgkmcnt(1)
	v_mul_f32_e32 v92, v29, v45
	v_lshlrev_b32_e32 v30, 2, v54
	v_mov_b32_e32 v31, v33
	v_fmac_f32_e32 v92, v28, v44
	ds_read_b128 v[60:63], v43 offset:41984
	ds_read_b128 v[64:67], v43 offset:46080
	ds_read_b128 v[68:71], v43 offset:50176
	ds_read_b128 v[72:75], v43 offset:54272
	ds_read_b128 v[76:79], v43 offset:58368
	ds_read_b128 v[80:83], v43 offset:62464
	v_lshl_add_u64 v[30:31], v[38:39], 0, v[30:31]
	v_fmac_f32_e32 v92, v26, v46
	global_load_dwordx4 v[84:87], v[30:31], off
	v_fmac_f32_e32 v92, v27, v47
	global_load_dwordx4 v[88:91], v32, s[8:9] offset:2048
	v_add_f32_e32 v108, v115, v92
	global_load_dwordx4 v[92:95], v[40:41], off offset:2048
	v_mul_f32_e32 v30, v23, v45
	v_fmac_f32_e32 v30, v22, v44
	v_fmac_f32_e32 v30, v20, v46
	v_fmac_f32_e32 v30, v21, v47
	v_add_f32_e32 v109, v116, v30
	s_waitcnt lgkmcnt(6)
	v_mul_f32_e32 v30, v29, v57
	v_fmac_f32_e32 v30, v28, v56
	v_fmac_f32_e32 v30, v26, v58
	v_fmac_f32_e32 v30, v27, v59
	v_add_f32_e32 v110, v117, v30
	v_mul_f32_e32 v30, v23, v57
	v_fmac_f32_e32 v30, v22, v56
	v_fmac_f32_e32 v30, v20, v58
	v_fmac_f32_e32 v30, v21, v59
	v_add_f32_e32 v111, v118, v30
	s_waitcnt lgkmcnt(5)
	v_mul_f32_e32 v30, v29, v61
	v_fmac_f32_e32 v30, v28, v60
	v_fmac_f32_e32 v30, v26, v62
	v_fmac_f32_e32 v30, v27, v63
	v_add_f32_e32 v112, v119, v30
	v_mul_f32_e32 v30, v23, v61
	v_fmac_f32_e32 v30, v22, v60
	v_fmac_f32_e32 v30, v20, v62
	v_fmac_f32_e32 v30, v21, v63
	v_add_f32_e32 v113, v120, v30
	s_waitcnt lgkmcnt(4)
	v_mul_f32_e32 v30, v29, v65
	v_fmac_f32_e32 v30, v28, v64
	v_fmac_f32_e32 v30, v26, v66
	v_fmac_f32_e32 v30, v27, v67
	v_add_f32_e32 v114, v121, v30
	v_mul_f32_e32 v30, v23, v65
	v_fmac_f32_e32 v30, v22, v64
	v_fmac_f32_e32 v30, v20, v66
	v_fmac_f32_e32 v30, v21, v67
	v_add_f32_e32 v115, v122, v30
	s_waitcnt lgkmcnt(3)
	v_mul_f32_e32 v30, v29, v69
	v_fmac_f32_e32 v30, v28, v68
	v_fmac_f32_e32 v30, v26, v70
	v_fmac_f32_e32 v30, v27, v71
	v_add_f32_e32 v116, v123, v30
	v_mul_f32_e32 v30, v23, v69
	v_fmac_f32_e32 v30, v22, v68
	v_fmac_f32_e32 v30, v20, v70
	v_fmac_f32_e32 v30, v21, v71
	v_add_f32_e32 v117, v124, v30
	s_waitcnt lgkmcnt(2)
	v_mul_f32_e32 v30, v29, v73
	v_fmac_f32_e32 v30, v28, v72
	v_fmac_f32_e32 v30, v26, v74
	v_fmac_f32_e32 v30, v27, v75
	v_add_f32_e32 v118, v125, v30
	v_mul_f32_e32 v30, v23, v73
	v_fmac_f32_e32 v30, v22, v72
	v_fmac_f32_e32 v30, v20, v74
	v_fmac_f32_e32 v30, v21, v75
	v_add_f32_e32 v119, v126, v30
	s_waitcnt lgkmcnt(1)
	v_mul_f32_e32 v30, v29, v77
	v_fmac_f32_e32 v30, v28, v76
	v_fmac_f32_e32 v30, v26, v78
	v_fmac_f32_e32 v30, v27, v79
	v_add_f32_e32 v120, v127, v30
	v_mul_f32_e32 v30, v23, v77
	s_waitcnt lgkmcnt(0)
	v_mul_f32_e32 v23, v23, v81
	v_fmac_f32_e32 v23, v22, v80
	v_fmac_f32_e32 v30, v22, v76
	v_mul_f32_e32 v29, v29, v81
	v_fmac_f32_e32 v23, v20, v82
	v_fmac_f32_e32 v30, v20, v78
	v_fmac_f32_e32 v29, v28, v80
	v_fmac_f32_e32 v23, v21, v83
	v_fmac_f32_e32 v30, v21, v79
	v_fmac_f32_e32 v29, v26, v82
	v_add_f32_e32 v82, v130, v23
	v_fmac_f32_e32 v29, v27, v83
	v_pk_mul_f32 v[26:27], v[8:9], v[42:43] op_sel_hi:[1,0]
	v_pk_mul_f32 v[8:9], v[10:11], v[42:43] op_sel_hi:[1,0]
	s_waitcnt vmcnt(2)
	v_pk_add_f32 v[20:21], v[86:87], 1.0 op_sel_hi:[1,0]
	v_pk_add_f32 v[22:23], v[84:85], 1.0 op_sel_hi:[1,0]
	s_waitcnt vmcnt(1)
	v_pk_mul_f32 v[20:21], v[90:91], v[20:21]
	v_pk_mul_f32 v[22:23], v[88:89], v[22:23]
	v_add_f32_e32 v122, v129, v29
	s_waitcnt vmcnt(0)
	v_pk_fma_f32 v[8:9], v[8:9], v[20:21], v[94:95]
	v_pk_fma_f32 v[10:11], v[26:27], v[22:23], v[92:93]
	v_lshlrev_b32_e32 v28, 1, v54
	v_mov_b32_e32 v29, v33
	v_add_f32_e32 v121, v128, v30
	v_cvt_pk_bf16_f32 v26, v10, v11
	v_cvt_pk_bf16_f32 v27, v8, v9
	v_lshl_add_u64 v[30:31], v[16:17], 0, v[28:29]
	global_store_dwordx2 v[30:31], v[26:27], off
	v_pk_mul_f32 v[26:27], v[12:13], v[24:25] op_sel_hi:[1,0]
	v_pk_mul_f32 v[12:13], v[14:15], v[24:25] op_sel_hi:[1,0]
	v_pk_fma_f32 v[14:15], v[26:27], v[22:23], v[92:93]
	v_pk_fma_f32 v[12:13], v[12:13], v[20:21], v[94:95]
	v_cvt_pk_bf16_f32 v26, v14, v15
	ds_read_b128 v[20:23], v43 offset:2048
	v_cvt_pk_bf16_f32 v27, v12, v13
	v_lshl_add_u64 v[28:29], v[18:19], 0, v[28:29]
	global_store_dwordx2 v[28:29], v[26:27], off
	ds_read_b128 v[26:29], v43 offset:6144
	s_waitcnt lgkmcnt(1)
	v_mul_f32_e32 v30, v21, v11
	v_mul_f32_e32 v21, v21, v15
	v_fmac_f32_e32 v30, v20, v10
	v_fmac_f32_e32 v21, v20, v14
	s_waitcnt lgkmcnt(0)
	v_mul_f32_e32 v20, v11, v27
	v_fmac_f32_e32 v20, v10, v26
	v_mul_f32_e32 v27, v15, v27
	v_fmac_f32_e32 v21, v22, v12
	v_fmac_f32_e32 v20, v8, v28
	v_fmac_f32_e32 v27, v14, v26
	v_fmac_f32_e32 v30, v22, v8
	v_fmac_f32_e32 v21, v23, v13
	v_fmac_f32_e32 v20, v9, v29
	v_fmac_f32_e32 v27, v12, v28
	v_fmac_f32_e32 v30, v23, v9
	v_add_f32_e32 v48, v48, v21
	v_add_f32_e32 v49, v49, v20
	ds_read_b128 v[20:23], v43 offset:10240
	v_fmac_f32_e32 v27, v13, v29
	v_add_f32_e32 v83, v55, v27
	ds_read_b128 v[26:29], v43 offset:14336
	v_add_f32_e32 v25, v25, v30
	s_waitcnt lgkmcnt(1)
	v_mul_f32_e32 v30, v11, v21
	v_mul_f32_e32 v21, v15, v21
	v_fmac_f32_e32 v30, v10, v20
	v_fmac_f32_e32 v21, v14, v20
	s_waitcnt lgkmcnt(0)
	v_mul_f32_e32 v20, v11, v27
	v_fmac_f32_e32 v20, v10, v26
	v_mul_f32_e32 v27, v15, v27
	v_fmac_f32_e32 v21, v12, v22
	v_fmac_f32_e32 v20, v8, v28
	v_fmac_f32_e32 v27, v14, v26
	v_fmac_f32_e32 v30, v8, v22
	v_fmac_f32_e32 v21, v13, v23
	v_fmac_f32_e32 v20, v9, v29
	v_fmac_f32_e32 v27, v12, v28
	v_fmac_f32_e32 v30, v9, v23
	v_add_f32_e32 v85, v97, v21
	v_add_f32_e32 v86, v98, v20
	ds_read_b128 v[20:23], v43 offset:18432
	v_fmac_f32_e32 v27, v13, v29
	v_add_f32_e32 v87, v99, v27
	ds_read_b128 v[26:29], v43 offset:22528
	v_add_f32_e32 v84, v96, v30
	s_waitcnt lgkmcnt(1)
	v_mul_f32_e32 v30, v11, v21
	v_mul_f32_e32 v21, v15, v21
	v_fmac_f32_e32 v30, v10, v20
	v_fmac_f32_e32 v21, v14, v20
	s_waitcnt lgkmcnt(0)
	v_mul_f32_e32 v20, v11, v27
	v_fmac_f32_e32 v20, v10, v26
	v_mul_f32_e32 v27, v15, v27
	v_fmac_f32_e32 v21, v12, v22
	v_fmac_f32_e32 v20, v8, v28
	v_fmac_f32_e32 v27, v14, v26
	v_fmac_f32_e32 v30, v8, v22
	v_fmac_f32_e32 v21, v13, v23
	v_fmac_f32_e32 v20, v9, v29
	v_fmac_f32_e32 v27, v12, v28
	v_fmac_f32_e32 v30, v9, v23
	v_add_f32_e32 v89, v101, v21
	v_add_f32_e32 v90, v102, v20
	ds_read_b128 v[20:23], v43 offset:26624
	v_fmac_f32_e32 v27, v13, v29
	v_add_f32_e32 v91, v103, v27
	ds_read_b128 v[26:29], v43 offset:30720
	v_add_f32_e32 v88, v100, v30
	s_waitcnt lgkmcnt(1)
	v_mul_f32_e32 v30, v11, v21
	v_mul_f32_e32 v21, v15, v21
	v_fmac_f32_e32 v30, v10, v20
	v_fmac_f32_e32 v21, v14, v20
	s_waitcnt lgkmcnt(0)
	v_mul_f32_e32 v20, v11, v27
	v_mul_f32_e32 v27, v15, v27
	v_fmac_f32_e32 v20, v10, v26
	v_fmac_f32_e32 v27, v14, v26
	v_fmac_f32_e32 v21, v12, v22
	v_fmac_f32_e32 v20, v8, v28
	v_fmac_f32_e32 v27, v12, v28
	v_fmac_f32_e32 v30, v8, v22
	v_fmac_f32_e32 v21, v13, v23
	v_fmac_f32_e32 v20, v9, v29
	v_fmac_f32_e32 v27, v13, v29
	v_fmac_f32_e32 v30, v9, v23
	v_add_f32_e32 v93, v105, v21
	v_add_f32_e32 v94, v106, v20
	ds_read_b128 v[20:23], v43 offset:34816
	v_add_f32_e32 v95, v107, v27
	ds_read_b128 v[26:29], v43 offset:38912
	ds_read_b128 v[44:47], v43 offset:43008
	ds_read_b128 v[54:57], v43 offset:47104
	ds_read_b128 v[58:61], v43 offset:51200
	ds_read_b128 v[62:65], v43 offset:55296
	ds_read_b128 v[66:69], v43 offset:59392
	ds_read_b128 v[70:73], v43 offset:63488
	global_load_dwordx4 v[74:77], v32, s[8:9] offset:3072
	v_lshlrev_b32_e32 v32, 2, v53
	v_add_f32_e32 v92, v104, v30
	v_lshl_add_u64 v[30:31], v[38:39], 0, v[32:33]
	global_load_dwordx4 v[78:81], v[30:31], off
	s_waitcnt lgkmcnt(7)
	v_mul_f32_e32 v96, v11, v21
	global_load_dwordx4 v[38:41], v[40:41], off offset:3072
	v_mul_f32_e32 v21, v15, v21
	v_fmac_f32_e32 v21, v14, v20
	v_fmac_f32_e32 v21, v12, v22
	s_waitcnt lgkmcnt(2)
	v_mul_f32_e32 v32, v11, v63
	v_fmac_f32_e32 v96, v10, v20
	v_fmac_f32_e32 v21, v13, v23
	v_fmac_f32_e32 v32, v10, v62
	v_fmac_f32_e32 v96, v8, v22
	v_add_f32_e32 v20, v109, v21
	v_mul_f32_e32 v21, v11, v27
	v_mul_f32_e32 v22, v15, v27
	v_fmac_f32_e32 v32, v8, v64
	v_fmac_f32_e32 v96, v9, v23
	v_fmac_f32_e32 v21, v10, v26
	v_fmac_f32_e32 v22, v14, v26
	v_mul_f32_e32 v23, v11, v45
	v_mul_f32_e32 v26, v15, v45
	v_fmac_f32_e32 v32, v9, v65
	v_fmac_f32_e32 v23, v10, v44
	v_fmac_f32_e32 v26, v14, v44
	v_add_f32_e32 v44, v118, v32
	v_mul_f32_e32 v32, v15, v63
	v_fmac_f32_e32 v32, v14, v62
	v_fmac_f32_e32 v32, v12, v64
	v_fmac_f32_e32 v21, v8, v28
	v_fmac_f32_e32 v22, v12, v28
	v_fmac_f32_e32 v32, v13, v65
	v_fmac_f32_e32 v21, v9, v29
	v_fmac_f32_e32 v22, v13, v29
	v_mul_f32_e32 v27, v11, v55
	v_mul_f32_e32 v29, v11, v59
	v_add_f32_e32 v45, v119, v32
	s_waitcnt lgkmcnt(1)
	v_mul_f32_e32 v32, v11, v67
	s_waitcnt lgkmcnt(0)
	v_mul_f32_e32 v11, v11, v71
	v_fmac_f32_e32 v27, v10, v54
	v_fmac_f32_e32 v29, v10, v58
	v_fmac_f32_e32 v32, v10, v66
	v_fmac_f32_e32 v11, v10, v70
	v_fmac_f32_e32 v23, v8, v46
	v_fmac_f32_e32 v27, v8, v56
	v_fmac_f32_e32 v29, v8, v60
	v_fmac_f32_e32 v32, v8, v68
	v_fmac_f32_e32 v11, v8, v72
	v_mul_f32_e32 v8, v15, v71
	v_fmac_f32_e32 v32, v9, v69
	v_fmac_f32_e32 v8, v14, v70
	v_fmac_f32_e32 v26, v12, v46
	v_mul_f32_e32 v28, v15, v55
	v_mul_f32_e32 v31, v15, v59
	v_add_f32_e32 v46, v120, v32
	v_mul_f32_e32 v32, v15, v67
	v_fmac_f32_e32 v8, v12, v72
	v_fmac_f32_e32 v28, v14, v54
	v_fmac_f32_e32 v31, v14, v58
	v_fmac_f32_e32 v32, v14, v66
	v_fmac_f32_e32 v11, v9, v73
	v_fmac_f32_e32 v8, v13, v73
	v_fmac_f32_e32 v23, v9, v47
	v_fmac_f32_e32 v27, v9, v57
	v_fmac_f32_e32 v28, v12, v56
	v_fmac_f32_e32 v29, v9, v61
	v_fmac_f32_e32 v31, v12, v60
	v_fmac_f32_e32 v32, v12, v68
	v_add_f32_e32 v54, v122, v11
	v_add_f32_e32 v55, v82, v8
	v_fmac_f32_e32 v26, v13, v47
	v_fmac_f32_e32 v28, v13, v57
	v_fmac_f32_e32 v31, v13, v61
	v_fmac_f32_e32 v32, v13, v69
	v_pk_mul_f32 v[12:13], v[0:1], v[42:43] op_sel_hi:[1,0]
	v_pk_mul_f32 v[0:1], v[2:3], v[42:43] op_sel_hi:[1,0]
	v_add_f32_e32 v47, v121, v32
	v_lshlrev_b32_e32 v32, 1, v53
	v_lshl_add_u64 v[14:15], v[16:17], 0, v[32:33]
	v_add_f32_e32 v21, v110, v21
	v_add_f32_e32 v22, v111, v22
	v_add_f32_e32 v30, v108, v96
	s_waitcnt vmcnt(1)
	v_pk_add_f32 v[8:9], v[80:81], 1.0 op_sel_hi:[1,0]
	v_pk_add_f32 v[10:11], v[78:79], 1.0 op_sel_hi:[1,0]
	v_pk_mul_f32 v[8:9], v[76:77], v[8:9]
	v_pk_mul_f32 v[10:11], v[74:75], v[10:11]
	s_waitcnt vmcnt(0)
	v_pk_fma_f32 v[0:1], v[0:1], v[8:9], v[40:41]
	v_pk_fma_f32 v[2:3], v[12:13], v[10:11], v[38:39]
	v_cvt_pk_bf16_f32 v13, v0, v1
	v_cvt_pk_bf16_f32 v12, v2, v3
	global_store_dwordx2 v[14:15], v[12:13], off
	v_pk_mul_f32 v[12:13], v[4:5], v[24:25] op_sel_hi:[1,0]
	v_pk_mul_f32 v[4:5], v[6:7], v[24:25] op_sel_hi:[1,0]
	v_pk_fma_f32 v[6:7], v[12:13], v[10:11], v[38:39]
	v_pk_fma_f32 v[4:5], v[4:5], v[8:9], v[40:41]
	v_cvt_pk_bf16_f32 v12, v6, v7
	ds_read_b128 v[8:11], v43 offset:3072
	v_cvt_pk_bf16_f32 v13, v4, v5
	v_lshl_add_u64 v[14:15], v[18:19], 0, v[32:33]
	global_store_dwordx2 v[14:15], v[12:13], off
	s_add_i32 s38, s37, s56
	s_cmpk_lt_i32 s38, 0x600
	s_cbranch_scc0 .Lp1_pf_done
	s_add_i32 s43, s30, s31
	s_cmpk_lt_i32 s38, 0x200
	s_cselect_b32 s40, s12, s14
	s_cselect_b32 s41, s13, s15
	s_cselect_b32 s42, 0, 0x2000
	s_sub_i32 s39, s43, s42
	s_lshl_b32 s39, s39, 12
	s_add_u32 s40, s40, s39
	s_addc_u32 s41, s41, 0
	global_load_dwordx4 v[188:191], v252, s[40:41]
	global_load_dwordx4 v[192:195], v252, s[40:41] offset:1024
	global_load_dwordx4 v[196:199], v252, s[40:41] offset:2048
	global_load_dwordx4 v[200:203], v252, s[40:41] offset:3072
	global_load_dwordx4 v[204:207], v253, s[40:41]
	global_load_dwordx4 v[208:211], v253, s[40:41] offset:1024
	global_load_dwordx4 v[212:215], v253, s[40:41] offset:2048
	global_load_dwordx4 v[216:219], v253, s[40:41] offset:3072
.Lp1_pf_done:
	ds_read_b128 v[12:15], v43 offset:7168
	s_waitcnt lgkmcnt(1)
	v_mul_f32_e32 v16, v9, v3
	v_mul_f32_e32 v9, v9, v7
	v_fmac_f32_e32 v16, v8, v2
	v_fmac_f32_e32 v9, v8, v6
	s_waitcnt lgkmcnt(0)
	v_mul_f32_e32 v8, v3, v13
	v_fmac_f32_e32 v8, v2, v12
	v_mul_f32_e32 v13, v7, v13
	v_fmac_f32_e32 v9, v10, v4
	v_fmac_f32_e32 v8, v0, v14
	v_fmac_f32_e32 v13, v6, v12
	v_fmac_f32_e32 v16, v10, v0
	v_fmac_f32_e32 v9, v11, v5
	v_fmac_f32_e32 v8, v1, v15
	v_fmac_f32_e32 v13, v4, v14
	v_fmac_f32_e32 v16, v11, v1
	v_add_f32_e32 v17, v48, v9
	v_add_f32_e32 v18, v49, v8
	ds_read_b128 v[8:11], v43 offset:11264
	v_fmac_f32_e32 v13, v5, v15
	v_add_f32_e32 v19, v83, v13
	ds_read_b128 v[12:15], v43 offset:15360
	v_add_f32_e32 v16, v25, v16
	s_waitcnt lgkmcnt(1)
	v_mul_f32_e32 v24, v3, v9
	v_mul_f32_e32 v9, v7, v9
	v_fmac_f32_e32 v24, v2, v8
	v_fmac_f32_e32 v9, v6, v8
	s_waitcnt lgkmcnt(0)
	v_mul_f32_e32 v8, v3, v13
	v_fmac_f32_e32 v8, v2, v12
	v_mul_f32_e32 v13, v7, v13
	v_fmac_f32_e32 v9, v4, v10
	v_fmac_f32_e32 v8, v0, v14
	v_fmac_f32_e32 v13, v6, v12
	v_fmac_f32_e32 v24, v0, v10
	v_fmac_f32_e32 v9, v5, v11
	v_fmac_f32_e32 v8, v1, v15
	v_fmac_f32_e32 v13, v4, v14
	v_fmac_f32_e32 v24, v1, v11
	v_add_f32_e32 v25, v85, v9
	v_add_f32_e32 v32, v86, v8
	ds_read_b128 v[8:11], v43 offset:19456
	v_fmac_f32_e32 v13, v5, v15
	v_add_f32_e32 v38, v87, v13
	ds_read_b128 v[12:15], v43 offset:23552
	v_add_f32_e32 v26, v113, v26
	s_waitcnt lgkmcnt(1)
	v_mul_f32_e32 v39, v3, v9
	v_mul_f32_e32 v9, v7, v9
	v_fmac_f32_e32 v39, v2, v8
	v_fmac_f32_e32 v9, v6, v8
	s_waitcnt lgkmcnt(0)
	v_mul_f32_e32 v8, v3, v13
	v_fmac_f32_e32 v8, v2, v12
	v_mul_f32_e32 v13, v7, v13
	v_fmac_f32_e32 v9, v4, v10
	v_fmac_f32_e32 v8, v0, v14
	v_fmac_f32_e32 v13, v6, v12
	v_fmac_f32_e32 v39, v0, v10
	v_fmac_f32_e32 v9, v5, v11
	v_fmac_f32_e32 v8, v1, v15
	v_fmac_f32_e32 v13, v4, v14
	v_fmac_f32_e32 v39, v1, v11
	v_add_f32_e32 v40, v89, v9
	v_add_f32_e32 v41, v90, v8
	ds_read_b128 v[8:11], v43 offset:27648
	v_fmac_f32_e32 v13, v5, v15
	v_add_f32_e32 v42, v91, v13
	ds_read_b128 v[12:15], v43 offset:31744
	v_add_f32_e32 v27, v114, v27
	s_waitcnt lgkmcnt(1)
	v_mul_f32_e32 v48, v3, v9
	v_mul_f32_e32 v9, v7, v9
	v_fmac_f32_e32 v48, v2, v8
	v_fmac_f32_e32 v9, v6, v8
	s_waitcnt lgkmcnt(0)
	v_mul_f32_e32 v8, v3, v13
	v_fmac_f32_e32 v8, v2, v12
	v_mul_f32_e32 v13, v7, v13
	v_fmac_f32_e32 v9, v4, v10
	v_fmac_f32_e32 v8, v0, v14
	v_fmac_f32_e32 v13, v6, v12
	v_fmac_f32_e32 v48, v0, v10
	v_fmac_f32_e32 v9, v5, v11
	v_fmac_f32_e32 v8, v1, v15
	v_fmac_f32_e32 v13, v4, v14
	v_fmac_f32_e32 v48, v1, v11
	v_add_f32_e32 v49, v93, v9
	v_add_f32_e32 v53, v94, v8
	ds_read_b128 v[8:11], v43 offset:35840
	v_fmac_f32_e32 v13, v5, v15
	v_add_f32_e32 v56, v95, v13
	ds_read_b128 v[12:15], v43 offset:39936
	v_add_f32_e32 v28, v115, v28
	s_waitcnt lgkmcnt(1)
	v_mul_f32_e32 v57, v3, v9
	v_mul_f32_e32 v9, v7, v9
	v_fmac_f32_e32 v57, v2, v8
	v_fmac_f32_e32 v9, v6, v8
	s_waitcnt lgkmcnt(0)
	v_mul_f32_e32 v8, v3, v13
	v_fmac_f32_e32 v8, v2, v12
	v_mul_f32_e32 v13, v7, v13
	v_fmac_f32_e32 v9, v4, v10
	v_fmac_f32_e32 v8, v0, v14
	v_fmac_f32_e32 v13, v6, v12
	v_fmac_f32_e32 v57, v0, v10
	v_fmac_f32_e32 v9, v5, v11
	v_fmac_f32_e32 v8, v1, v15
	v_fmac_f32_e32 v13, v4, v14
	v_fmac_f32_e32 v57, v1, v11
	v_add_f32_e32 v20, v20, v9
	v_add_f32_e32 v21, v21, v8
	ds_read_b128 v[8:11], v43 offset:44032
	v_fmac_f32_e32 v13, v5, v15
	v_add_f32_e32 v22, v22, v13
	ds_read_b128 v[12:15], v43 offset:48128
	v_add_f32_e32 v30, v30, v57
	s_waitcnt lgkmcnt(1)
	v_mul_f32_e32 v57, v3, v9
	v_mul_f32_e32 v9, v7, v9
	v_fmac_f32_e32 v57, v2, v8
	v_fmac_f32_e32 v9, v6, v8
	s_waitcnt lgkmcnt(0)
	v_mul_f32_e32 v8, v3, v13
	v_fmac_f32_e32 v8, v2, v12
	v_mul_f32_e32 v13, v7, v13
	v_fmac_f32_e32 v9, v4, v10
	v_fmac_f32_e32 v8, v0, v14
	v_fmac_f32_e32 v13, v6, v12
	v_fmac_f32_e32 v57, v0, v10
	v_fmac_f32_e32 v9, v5, v11
	v_fmac_f32_e32 v8, v1, v15
	v_fmac_f32_e32 v13, v4, v14
	v_fmac_f32_e32 v57, v1, v11
	v_add_f32_e32 v26, v26, v9
	v_add_f32_e32 v27, v27, v8
	ds_read_b128 v[8:11], v43 offset:52224
	v_fmac_f32_e32 v13, v5, v15
	v_add_f32_e32 v28, v28, v13
	ds_read_b128 v[12:15], v43 offset:56320
	v_add_f32_e32 v23, v112, v23
	v_add_f32_e32 v23, v23, v57
	s_waitcnt lgkmcnt(1)
	v_mul_f32_e32 v57, v3, v9
	v_mul_f32_e32 v9, v7, v9
	v_fmac_f32_e32 v57, v2, v8
	v_fmac_f32_e32 v9, v6, v8
	s_waitcnt lgkmcnt(0)
	v_mul_f32_e32 v8, v3, v13
	v_mul_f32_e32 v13, v7, v13
	v_fmac_f32_e32 v8, v2, v12
	v_fmac_f32_e32 v13, v6, v12
	v_fmac_f32_e32 v9, v4, v10
	v_fmac_f32_e32 v8, v0, v14
	v_fmac_f32_e32 v13, v4, v14
	v_add_f32_e32 v31, v117, v31
	v_fmac_f32_e32 v57, v0, v10
	v_fmac_f32_e32 v9, v5, v11
	v_fmac_f32_e32 v8, v1, v15
	v_fmac_f32_e32 v13, v5, v15
	v_fmac_f32_e32 v57, v1, v11
	v_add_f32_e32 v31, v31, v9
	v_add_f32_e32 v44, v44, v8
	ds_read_b128 v[8:11], v43 offset:60416
	v_add_f32_e32 v45, v45, v13
	ds_read_b128 v[12:15], v43 offset:64512
	v_permlane16_swap_b32_e32 v16, v17
	s_waitcnt lgkmcnt(1)
	v_mul_f32_e32 v43, v3, v9
	v_fmac_f32_e32 v43, v2, v8
	s_waitcnt lgkmcnt(0)
	v_mul_f32_e32 v3, v3, v13
	v_fmac_f32_e32 v3, v2, v12
	v_fmac_f32_e32 v43, v0, v10
	v_fmac_f32_e32 v3, v0, v14
	v_fmac_f32_e32 v43, v1, v11
	v_fmac_f32_e32 v3, v1, v15
	v_mul_f32_e32 v1, v7, v13
	v_fmac_f32_e32 v1, v6, v12
	v_fmac_f32_e32 v1, v4, v14
	v_fmac_f32_e32 v1, v5, v15
	v_mul_f32_e32 v9, v7, v9
	v_add_f32_e32 v0, v54, v3
	v_add_f32_e32 v1, v55, v1
	v_fmac_f32_e32 v9, v6, v8
	s_nop 0
	v_permlane16_swap_b32_e32 v0, v1
	v_fmac_f32_e32 v9, v4, v10
	v_permlane16_swap_b32_e32 v30, v20
	v_add_f32_e32 v0, v0, v1
	v_and_b32_e32 v1, 8, v37
	v_add_f32_e32 v24, v84, v24
	v_fmac_f32_e32 v9, v5, v11
	v_add_f32_e32 v2, v16, v17
	v_permlane16_swap_b32_e32 v18, v19
	v_add_f32_e32 v11, v30, v20
	v_permlane16_swap_b32_e32 v21, v22
	v_cmp_eq_u32_e32 vcc, 0, v1
	v_add_f32_e32 v29, v116, v29
	v_add_f32_e32 v3, v18, v19
	v_permlane16_swap_b32_e32 v24, v25
	v_add_f32_e32 v12, v21, v22
	v_permlane16_swap_b32_e32 v23, v26
	v_cndmask_b32_e32 v1, v2, v11, vcc
	v_cndmask_b32_e32 v2, v11, v2, vcc
	v_add_f32_e32 v39, v88, v39
	v_add_f32_e32 v29, v29, v57
	v_add_f32_e32 v4, v24, v25
	v_permlane16_swap_b32_e32 v32, v38
	v_add_f32_e32 v13, v23, v26
	v_permlane16_swap_b32_e32 v27, v28
	v_add_f32_dpp v1, v1, v2 row_ror:8 row_mask:0xf bank_mask:0xf bound_ctrl:1
	v_cndmask_b32_e32 v2, v3, v12, vcc
	v_cndmask_b32_e32 v3, v12, v3, vcc
	v_add_f32_e32 v5, v32, v38
	v_permlane16_swap_b32_e32 v39, v40
	v_add_f32_e32 v14, v27, v28
	v_permlane16_swap_b32_e32 v29, v31
	v_add_f32_dpp v2, v2, v3 row_ror:8 row_mask:0xf bank_mask:0xf bound_ctrl:1
	v_cndmask_b32_e32 v3, v4, v13, vcc
	v_cndmask_b32_e32 v4, v13, v4, vcc
	v_add_f32_e32 v48, v92, v48
	v_add_f32_e32 v43, v46, v43
	v_add_f32_e32 v8, v47, v9
	v_add_f32_e32 v6, v39, v40
	v_permlane16_swap_b32_e32 v41, v42
	v_add_f32_e32 v15, v29, v31
	v_permlane16_swap_b32_e32 v44, v45
	v_add_f32_dpp v3, v3, v4 row_ror:8 row_mask:0xf bank_mask:0xf bound_ctrl:1
	v_cndmask_b32_e32 v4, v5, v14, vcc
	v_cndmask_b32_e32 v5, v14, v5, vcc
	v_add_f32_e32 v7, v41, v42
	v_permlane16_swap_b32_e32 v48, v49
	v_add_f32_e32 v16, v44, v45
	v_permlane16_swap_b32_e32 v43, v8
	v_add_f32_dpp v4, v4, v5 row_ror:8 row_mask:0xf bank_mask:0xf bound_ctrl:1
	v_cndmask_b32_e32 v5, v6, v15, vcc
	v_cndmask_b32_e32 v6, v15, v6, vcc
	v_add_f32_e32 v9, v48, v49
	v_add_f32_e32 v8, v43, v8
	v_add_f32_dpp v5, v5, v6 row_ror:8 row_mask:0xf bank_mask:0xf bound_ctrl:1
	v_cndmask_b32_e32 v6, v7, v16, vcc
	v_cndmask_b32_e32 v7, v16, v7, vcc
	v_and_b32_e32 v11, 64, v51
	v_add_u32_e32 v11, 64, v11
	v_add_f32_dpp v6, v6, v7 row_ror:8 row_mask:0xf bank_mask:0xf bound_ctrl:1
	v_cndmask_b32_e32 v7, v9, v8, vcc
	v_cndmask_b32_e32 v8, v8, v9, vcc
	v_xor_b32_e32 v9, 4, v51
	v_cmp_lt_i32_e64 s[4:5], v9, v11
	v_add_f32_dpp v7, v7, v8 row_ror:8 row_mask:0xf bank_mask:0xf bound_ctrl:1
	v_and_b32_e32 v8, 4, v37
	v_cndmask_b32_e64 v9, v51, v9, s[4:5]
	v_cmp_eq_u32_e64 s[4:5], 0, v8
	v_lshlrev_b32_e32 v9, 2, v9
	v_permlane16_swap_b32_e32 v53, v56
	v_cndmask_b32_e64 v8, v1, v5, s[4:5]
	ds_bpermute_b32 v8, v9, v8
	v_add_f32_e32 v10, v53, v56
	v_cndmask_b32_e32 v11, v10, v0, vcc
	v_cndmask_b32_e32 v0, v0, v10, vcc
	v_cndmask_b32_e64 v1, v5, v1, s[4:5]
	s_waitcnt lgkmcnt(0)
	v_add_f32_e32 v1, v1, v8
	v_add_f32_dpp v0, v11, v0 row_ror:8 row_mask:0xf bank_mask:0xf bound_ctrl:1
	v_cndmask_b32_e64 v5, v2, v6, s[4:5]
	v_cndmask_b32_e64 v2, v6, v2, s[4:5]
	v_cndmask_b32_e64 v6, v3, v7, s[4:5]
	v_cndmask_b32_e64 v8, v4, v0, s[4:5]
	ds_bpermute_b32 v5, v9, v5
	ds_bpermute_b32 v6, v9, v6
	ds_bpermute_b32 v8, v9, v8
	v_cndmask_b32_e64 v3, v7, v3, s[4:5]
	v_cndmask_b32_e64 v0, v0, v4, s[4:5]
	v_and_b32_e32 v4, 2, v37
	s_waitcnt lgkmcnt(2)
	v_add_f32_e32 v2, v2, v5
	s_waitcnt lgkmcnt(1)
	v_add_f32_e32 v3, v3, v6
	s_waitcnt lgkmcnt(0)
	v_add_f32_e32 v0, v0, v8
	v_cmp_eq_u32_e32 vcc, 0, v4
	s_nop 1
	v_cndmask_b32_e32 v4, v1, v3, vcc
	v_cndmask_b32_e32 v1, v3, v1, vcc
	v_cndmask_b32_e32 v3, v2, v0, vcc
	v_cndmask_b32_e32 v0, v0, v2, vcc
	v_and_b32_e32 v2, 1, v37
	v_add_f32_dpp v1, v4, v1 quad_perm:[2,3,0,1] row_mask:0xf bank_mask:0xf bound_ctrl:1
	v_add_f32_dpp v0, v3, v0 quad_perm:[2,3,0,1] row_mask:0xf bank_mask:0xf bound_ctrl:1
	v_cmp_eq_u32_e32 vcc, 0, v2
	s_nop 1
	v_cndmask_b32_e32 v2, v1, v0, vcc
	v_cndmask_b32_e32 v0, v0, v1, vcc
	v_cmp_gt_u32_e32 vcc, 32, v52
	s_nop 0
	v_add_f32_dpp v0, v2, v0 quad_perm:[1,0,3,2] row_mask:0xf bank_mask:0xf bound_ctrl:1
	v_mov_b32_e32 v1, v0
	s_nop 1
	v_permlane32_swap_b32_e32 v0, v1
	s_and_saveexec_b64 s[4:5], vcc
	s_cbranch_execz .LBB0_129
	v_and_b32_e32 v2, 15, v37
	v_lshlrev_b32_e32 v32, 2, v2
	v_lshl_add_u64 v[2:3], s[10:11], 0, v[32:33]
	v_add_co_u32_e32 v2, vcc, 0x4000, v2
	v_mov_b32_e32 v37, v33
	s_nop 0
	v_addc_co_u32_e32 v3, vcc, 0, v3, vcc
	v_add_f32_e32 v3, v0, v1
	v_lshlrev_b64 v[0:1], 6, v[34:35]
	v_lshl_add_u64 v[0:1], s[24:25], 0, v[0:1]
	v_lshl_add_u64 v[0:1], v[0:1], 0, v[36:37]
	v_add_f32_e32 v2, v3, v251
	global_store_dword v[0:1], v2, off
	s_branch .LBB0_129
